# static s_setprio 1 for waves 0-3 (instead of 4-7) during the mixer phases
# baseline (speedup 1.0000x reference)
.LBB0_377:
	v_readfirstlane_b32 s98, v0
	s_nop 3
	s_lshr_b32 s98, s98, 6
	s_cmp_ge_u32 s98, 4
	s_cbranch_scc1 .Lprio_skip
	s_setprio 1
